# GEMM phases: per-cluster s_setprio toggling replaced by one static priority raise for waves 4..7 per phase
# speedup vs baseline: 1.0055x; 1.0055x over previous
.LBB0_86:
	s_or_b64 exec, exec, s[0:1]
	s_setprio 0
	v_readfirstlane_b32 s0, v180
	s_nop 1
	s_cmpk_lt_u32 s0, 0x100
	s_cbranch_scc1 .Lprio_86
	s_setprio 1
.Lprio_86:
	v_mov_b32_e32 v14, v180
	s_cmpk_lt_i32 s2, 0xc80
	s_waitcnt lgkmcnt(0)
	s_barrier
	s_movk_i32 s0, 0x400
	v_readfirstlane_b32 s8, v14
	s_cselect_b64 s[4:5], -1, 0
	s_cmpk_gt_i32 s2, 0xc7f
	s_cbranch_scc1 .LBB0_88
	s_ashr_i32 s1, s2, 31
	s_lshr_b32 s1, s1, 29
	s_add_i32 s1, s2, s1
	s_ashr_i32 s3, s1, 3
	s_and_b32 s1, s1, -8
	s_sub_i32 s1, s2, s1
	s_cmp_lt_i32 s1, 0
	s_movk_i32 s6, 0x191
	s_cselect_b32 s6, s6, 0x190
	s_mul_i32 s1, s6, s1
	s_add_i32 s1, s1, s3
	s_mul_hi_i32 s3, s1, 0x51eb851f
	s_lshr_b32 s6, s3, 31
	s_ashr_i32 s3, s3, 6
	s_add_i32 s3, s3, s6
	s_lshl_b32 s6, s3, 3
	s_mulk_i32 s3, 0xc8
	s_sub_i32 s1, s1, s3
	s_sext_i32_i16 s3, s1
	s_bfe_u32 s3, s3, 0x3001c
	s_add_i32 s3, s1, s3
	s_sext_i32_i16 s7, s3
	s_and_b32 s3, s3, 0xfff8
	s_sub_i32 s1, s1, s3
	s_sext_i32_i16 s1, s1
	s_add_i32 s3, s6, s1
	s_ashr_i32 s94, s7, 3

.LBB0_102:
	ds_read_b128 v[156:159], v152
	ds_read_b128 v[160:163], v152 offset:1024
	ds_read_b128 v[164:167], v152 offset:2048
	ds_read_b128 v[168:171], v152 offset:3072
	s_add_i32 vcc_hi, s80, 2
	s_add_u32 s82, s78, 0x80
	s_addc_u32 s81, s79, 0
	s_cmp_eq_u32 s92, s80
	s_cselect_b32 s80, s0, s82
	s_cselect_b32 s81, s1, s81
	s_cselect_b32 s83, s9, vcc_lo
	s_cselect_b32 s82, s8, s73
	v_lshl_add_u64 v[148:149], s[78:79], 0, v[140:141]
	s_add_i32 m0, s84, 0xc000
	ds_read_b128 v[172:175], v153
	ds_read_b128 v[176:179], v153 offset:1024
	ds_read_b128 v[182:185], v153 offset:2048
	ds_read_b128 v[186:189], v153 offset:3072
	ds_read_b128 v[190:193], v153 offset:4096
	ds_read_b128 v[194:197], v153 offset:5120
	ds_read_b128 v[198:201], v153 offset:6144
	ds_read_b128 v[202:205], v153 offset:7168
	global_load_lds_dwordx4 v[148:149], off
	v_lshl_add_u64 v[148:149], s[78:79], 0, v[142:143]
	s_add_i32 m0, s84, 0xe000
	s_nop 0
	global_load_lds_dwordx4 v[148:149], off
	s_waitcnt lgkmcnt(8)
	s_barrier
	s_waitcnt lgkmcnt(0)

	s_waitcnt lgkmcnt(0)
	v_mfma_f32_16x16x32_bf16 v[126:129], v[156:159], v[172:175], v[126:129]
	v_mfma_f32_16x16x32_bf16 v[122:125], v[164:167], v[172:175], v[122:125]
	v_mfma_f32_16x16x32_bf16 v[118:121], v[156:159], v[182:185], v[118:121]
	v_mfma_f32_16x16x32_bf16 v[114:117], v[164:167], v[182:185], v[114:117]
	v_mfma_f32_16x16x32_bf16 v[94:97], v[156:159], v[190:193], v[94:97]
	v_mfma_f32_16x16x32_bf16 v[90:93], v[164:167], v[190:193], v[90:93]
	v_mfma_f32_16x16x32_bf16 v[86:89], v[156:159], v[198:201], v[86:89]
	v_mfma_f32_16x16x32_bf16 v[82:85], v[164:167], v[198:201], v[82:85]
	v_mfma_f32_16x16x32_bf16 v[126:129], v[160:163], v[176:179], v[126:129]
	v_mfma_f32_16x16x32_bf16 v[122:125], v[168:171], v[176:179], v[122:125]
	v_mfma_f32_16x16x32_bf16 v[118:121], v[160:163], v[186:189], v[118:121]
	v_mfma_f32_16x16x32_bf16 v[114:117], v[168:171], v[186:189], v[114:117]
	v_mfma_f32_16x16x32_bf16 v[94:97], v[160:163], v[194:197], v[94:97]
	v_mfma_f32_16x16x32_bf16 v[90:93], v[168:171], v[194:197], v[90:93]
	v_mfma_f32_16x16x32_bf16 v[86:89], v[160:163], v[202:205], v[86:89]
	v_mfma_f32_16x16x32_bf16 v[82:85], v[168:171], v[202:205], v[82:85]

	s_barrier
	s_add_i32 s74, s16, s71
	v_lshl_add_u64 v[148:149], s[82:83], 0, v[132:133]
	s_mov_b32 m0, s74
	ds_read_b128 v[206:209], v154
	ds_read_b128 v[210:213], v154 offset:1024
	ds_read_b128 v[214:217], v154 offset:2048
	ds_read_b128 v[218:221], v154 offset:3072
	global_load_lds_dwordx4 v[148:149], off
	v_lshl_add_u64 v[222:223], s[82:83], 0, v[136:137]
	s_add_i32 m0, s74, 0x2000
	s_nop 0
	global_load_lds_dwordx4 v[222:223], off
	s_barrier
	s_waitcnt lgkmcnt(0)

	s_waitcnt lgkmcnt(0)
	v_mfma_f32_16x16x32_bf16 v[110:113], v[206:209], v[172:175], v[110:113]
	v_mfma_f32_16x16x32_bf16 v[106:109], v[214:217], v[172:175], v[106:109]
	v_mfma_f32_16x16x32_bf16 v[102:105], v[206:209], v[182:185], v[102:105]
	v_mfma_f32_16x16x32_bf16 v[98:101], v[214:217], v[182:185], v[98:101]
	v_mfma_f32_16x16x32_bf16 v[78:81], v[206:209], v[190:193], v[78:81]
	v_mfma_f32_16x16x32_bf16 v[74:77], v[214:217], v[190:193], v[74:77]
	v_mfma_f32_16x16x32_bf16 v[70:73], v[206:209], v[198:201], v[70:73]
	v_mfma_f32_16x16x32_bf16 v[66:69], v[214:217], v[198:201], v[66:69]
	v_mfma_f32_16x16x32_bf16 v[110:113], v[210:213], v[176:179], v[110:113]
	v_mfma_f32_16x16x32_bf16 v[106:109], v[218:221], v[176:179], v[106:109]
	v_mfma_f32_16x16x32_bf16 v[102:105], v[210:213], v[186:189], v[102:105]
	v_mfma_f32_16x16x32_bf16 v[98:101], v[218:221], v[186:189], v[98:101]
	v_mfma_f32_16x16x32_bf16 v[78:81], v[210:213], v[194:197], v[78:81]
	v_mfma_f32_16x16x32_bf16 v[74:77], v[218:221], v[194:197], v[74:77]
	v_mfma_f32_16x16x32_bf16 v[70:73], v[210:213], v[202:205], v[70:73]
	v_mfma_f32_16x16x32_bf16 v[66:69], v[218:221], v[202:205], v[66:69]

	s_mov_b32 m0, s84
	v_lshl_add_u64 v[224:225], s[80:81], 0, v[130:131]
	s_barrier
	ds_read_b128 v[172:175], v153 offset:16384
	ds_read_b128 v[176:179], v153 offset:17408
	ds_read_b128 v[182:185], v153 offset:18432
	ds_read_b128 v[186:189], v153 offset:19456
	ds_read_b128 v[190:193], v153 offset:20480
	ds_read_b128 v[194:197], v153 offset:21504
	ds_read_b128 v[198:201], v153 offset:22528
	ds_read_b128 v[202:205], v153 offset:23552
	global_load_lds_dwordx4 v[224:225], off
	v_lshl_add_u64 v[226:227], s[80:81], 0, v[134:135]
	s_mov_b32 m0, s85
	s_nop 0
	global_load_lds_dwordx4 v[226:227], off
	s_barrier
	s_waitcnt lgkmcnt(0)

	s_waitcnt lgkmcnt(0)
	v_mfma_f32_16x16x32_bf16 v[62:65], v[156:159], v[172:175], v[62:65]
	v_mfma_f32_16x16x32_bf16 v[58:61], v[164:167], v[172:175], v[58:61]
	v_mfma_f32_16x16x32_bf16 v[54:57], v[156:159], v[182:185], v[54:57]
	v_mfma_f32_16x16x32_bf16 v[50:53], v[164:167], v[182:185], v[50:53]
	v_mfma_f32_16x16x32_bf16 v[30:33], v[156:159], v[190:193], v[30:33]
	v_mfma_f32_16x16x32_bf16 v[26:29], v[164:167], v[190:193], v[26:29]
	v_mfma_f32_16x16x32_bf16 v[22:25], v[156:159], v[198:201], v[22:25]
	v_mfma_f32_16x16x32_bf16 v[18:21], v[164:167], v[198:201], v[18:21]
	v_mfma_f32_16x16x32_bf16 v[62:65], v[160:163], v[176:179], v[62:65]
	v_mfma_f32_16x16x32_bf16 v[58:61], v[168:171], v[176:179], v[58:61]
	v_mfma_f32_16x16x32_bf16 v[54:57], v[160:163], v[186:189], v[54:57]
	v_mfma_f32_16x16x32_bf16 v[50:53], v[168:171], v[186:189], v[50:53]
	v_mfma_f32_16x16x32_bf16 v[30:33], v[160:163], v[194:197], v[30:33]
	v_mfma_f32_16x16x32_bf16 v[26:29], v[168:171], v[194:197], v[26:29]
	v_mfma_f32_16x16x32_bf16 v[22:25], v[160:163], v[202:205], v[22:25]
	v_mfma_f32_16x16x32_bf16 v[18:21], v[168:171], v[202:205], v[18:21]

	s_barrier
	s_add_u32 s82, s82, s10
	s_addc_u32 s83, s83, s11
	s_add_i32 s74, s70, s71
	v_lshl_add_u64 v[228:229], s[82:83], 0, v[132:133]
	s_mov_b32 m0, s74
	v_lshl_add_u64 v[230:231], s[82:83], 0, v[136:137]
	global_load_lds_dwordx4 v[228:229], off
	s_add_i32 m0, s74, 0x2000
	s_nop 0
	global_load_lds_dwordx4 v[230:231], off
	s_waitcnt vmcnt(6)
	s_barrier

	v_mfma_f32_16x16x32_bf16 v[46:49], v[206:209], v[172:175], v[46:49]
	v_mfma_f32_16x16x32_bf16 v[42:45], v[214:217], v[172:175], v[42:45]
	v_mfma_f32_16x16x32_bf16 v[38:41], v[206:209], v[182:185], v[38:41]
	v_mfma_f32_16x16x32_bf16 v[34:37], v[214:217], v[182:185], v[34:37]
	v_mfma_f32_16x16x32_bf16 v[14:17], v[206:209], v[190:193], v[14:17]
	v_mfma_f32_16x16x32_bf16 v[10:13], v[214:217], v[190:193], v[10:13]
	v_mfma_f32_16x16x32_bf16 v[6:9], v[206:209], v[198:201], v[6:9]
	v_mfma_f32_16x16x32_bf16 v[2:5], v[214:217], v[198:201], v[2:5]
	v_mfma_f32_16x16x32_bf16 v[46:49], v[210:213], v[176:179], v[46:49]
	v_mfma_f32_16x16x32_bf16 v[42:45], v[218:221], v[176:179], v[42:45]
	v_mfma_f32_16x16x32_bf16 v[38:41], v[210:213], v[186:189], v[38:41]
	v_mfma_f32_16x16x32_bf16 v[34:37], v[218:221], v[186:189], v[34:37]
	v_mfma_f32_16x16x32_bf16 v[14:17], v[210:213], v[194:197], v[14:17]
	v_mfma_f32_16x16x32_bf16 v[10:13], v[218:221], v[194:197], v[10:13]
	v_mfma_f32_16x16x32_bf16 v[6:9], v[210:213], v[202:205], v[6:9]
	v_mfma_f32_16x16x32_bf16 v[2:5], v[218:221], v[202:205], v[2:5]

	s_add_i32 s74, 0, 0x18000
	v_add_u32_e32 v155, s74, v150
	s_barrier
	ds_read_b128 v[156:159], v155
	ds_read_b128 v[160:163], v155 offset:1024
	ds_read_b128 v[164:167], v155 offset:2048
	ds_read_b128 v[168:171], v155 offset:3072
	s_add_u32 s80, s80, s10
	s_addc_u32 s81, s81, s11
	s_mov_b32 m0, s86
	v_lshl_add_u64 v[206:207], s[80:81], 0, v[130:131]
	ds_read_b128 v[172:175], v153 offset:32768
	ds_read_b128 v[176:179], v153 offset:33792
	ds_read_b128 v[182:185], v153 offset:34816
	ds_read_b128 v[186:189], v153 offset:35840
	ds_read_b128 v[190:193], v153 offset:36864
	ds_read_b128 v[194:197], v153 offset:37888
	ds_read_b128 v[198:201], v153 offset:38912
	ds_read_b128 v[202:205], v153 offset:39936
	global_load_lds_dwordx4 v[206:207], off
	v_lshl_add_u64 v[206:207], s[80:81], 0, v[134:135]
	s_mov_b32 m0, s87
	s_nop 0
	global_load_lds_dwordx4 v[206:207], off
	s_waitcnt lgkmcnt(8)
	s_barrier
	s_waitcnt lgkmcnt(0)

	s_waitcnt lgkmcnt(0)
	v_mfma_f32_16x16x32_bf16 v[126:129], v[156:159], v[172:175], v[126:129]
	v_mfma_f32_16x16x32_bf16 v[122:125], v[164:167], v[172:175], v[122:125]
	v_mfma_f32_16x16x32_bf16 v[118:121], v[156:159], v[182:185], v[118:121]
	v_mfma_f32_16x16x32_bf16 v[114:117], v[164:167], v[182:185], v[114:117]
	v_mfma_f32_16x16x32_bf16 v[94:97], v[156:159], v[190:193], v[94:97]
	v_mfma_f32_16x16x32_bf16 v[90:93], v[164:167], v[190:193], v[90:93]
	v_mfma_f32_16x16x32_bf16 v[86:89], v[156:159], v[198:201], v[86:89]
	v_mfma_f32_16x16x32_bf16 v[82:85], v[164:167], v[198:201], v[82:85]
	v_mfma_f32_16x16x32_bf16 v[126:129], v[160:163], v[176:179], v[126:129]
	v_mfma_f32_16x16x32_bf16 v[122:125], v[168:171], v[176:179], v[122:125]
	v_mfma_f32_16x16x32_bf16 v[118:121], v[160:163], v[186:189], v[118:121]
	v_mfma_f32_16x16x32_bf16 v[114:117], v[168:171], v[186:189], v[114:117]
	v_mfma_f32_16x16x32_bf16 v[94:97], v[160:163], v[194:197], v[94:97]
	v_mfma_f32_16x16x32_bf16 v[90:93], v[168:171], v[194:197], v[90:93]
	v_mfma_f32_16x16x32_bf16 v[86:89], v[160:163], v[202:205], v[86:89]
	v_mfma_f32_16x16x32_bf16 v[82:85], v[168:171], v[202:205], v[82:85]

	s_barrier
	s_add_i32 s75, 0, 0x1c000
	s_add_i32 s74, s74, s71
	v_add_u32_e32 v155, s75, v150
	v_lshl_add_u64 v[148:149], v[148:149], 0, s[14:15]
	s_mov_b32 m0, s74
	ds_read_b128 v[206:209], v155
	ds_read_b128 v[210:213], v155 offset:1024
	ds_read_b128 v[214:217], v155 offset:2048
	ds_read_b128 v[218:221], v155 offset:3072
	global_load_lds_dwordx4 v[148:149], off
	v_lshl_add_u64 v[148:149], v[222:223], 0, s[14:15]
	s_add_i32 m0, s74, 0x2000
	s_nop 0
	global_load_lds_dwordx4 v[148:149], off
	s_barrier
	s_waitcnt lgkmcnt(0)

	s_waitcnt lgkmcnt(0)
	v_mfma_f32_16x16x32_bf16 v[110:113], v[206:209], v[172:175], v[110:113]
	v_mfma_f32_16x16x32_bf16 v[106:109], v[214:217], v[172:175], v[106:109]
	v_mfma_f32_16x16x32_bf16 v[102:105], v[206:209], v[182:185], v[102:105]
	v_mfma_f32_16x16x32_bf16 v[98:101], v[214:217], v[182:185], v[98:101]
	v_mfma_f32_16x16x32_bf16 v[78:81], v[206:209], v[190:193], v[78:81]
	v_mfma_f32_16x16x32_bf16 v[74:77], v[214:217], v[190:193], v[74:77]
	v_mfma_f32_16x16x32_bf16 v[70:73], v[206:209], v[198:201], v[70:73]
	v_mfma_f32_16x16x32_bf16 v[66:69], v[214:217], v[198:201], v[66:69]
	v_mfma_f32_16x16x32_bf16 v[110:113], v[210:213], v[176:179], v[110:113]
	v_mfma_f32_16x16x32_bf16 v[106:109], v[218:221], v[176:179], v[106:109]
	v_mfma_f32_16x16x32_bf16 v[102:105], v[210:213], v[186:189], v[102:105]
	v_mfma_f32_16x16x32_bf16 v[98:101], v[218:221], v[186:189], v[98:101]
	v_mfma_f32_16x16x32_bf16 v[78:81], v[210:213], v[194:197], v[78:81]
	v_mfma_f32_16x16x32_bf16 v[74:77], v[218:221], v[194:197], v[74:77]
	v_mfma_f32_16x16x32_bf16 v[70:73], v[210:213], v[202:205], v[70:73]
	v_mfma_f32_16x16x32_bf16 v[66:69], v[218:221], v[202:205], v[66:69]

	s_mov_b32 m0, s89
	v_lshl_add_u64 v[148:149], v[224:225], 0, s[14:15]
	s_barrier
	ds_read_b128 v[172:175], v153 offset:49152
	ds_read_b128 v[176:179], v153 offset:50176
	ds_read_b128 v[182:185], v153 offset:51200
	ds_read_b128 v[186:189], v153 offset:52224
	ds_read_b128 v[190:193], v153 offset:53248
	ds_read_b128 v[194:197], v153 offset:54272
	ds_read_b128 v[198:201], v153 offset:55296
	ds_read_b128 v[202:205], v153 offset:56320
	global_load_lds_dwordx4 v[148:149], off
	v_lshl_add_u64 v[148:149], v[226:227], 0, s[14:15]
	s_mov_b32 m0, s90
	s_nop 0
	global_load_lds_dwordx4 v[148:149], off
	s_barrier
	s_waitcnt lgkmcnt(0)

	s_waitcnt lgkmcnt(0)
	v_mfma_f32_16x16x32_bf16 v[62:65], v[156:159], v[172:175], v[62:65]
	v_mfma_f32_16x16x32_bf16 v[58:61], v[164:167], v[172:175], v[58:61]
	v_mfma_f32_16x16x32_bf16 v[54:57], v[156:159], v[182:185], v[54:57]
	v_mfma_f32_16x16x32_bf16 v[50:53], v[164:167], v[182:185], v[50:53]
	v_mfma_f32_16x16x32_bf16 v[30:33], v[156:159], v[190:193], v[30:33]
	v_mfma_f32_16x16x32_bf16 v[26:29], v[164:167], v[190:193], v[26:29]
	v_mfma_f32_16x16x32_bf16 v[22:25], v[156:159], v[198:201], v[22:25]
	v_mfma_f32_16x16x32_bf16 v[18:21], v[164:167], v[198:201], v[18:21]
	v_mfma_f32_16x16x32_bf16 v[62:65], v[160:163], v[176:179], v[62:65]
	v_mfma_f32_16x16x32_bf16 v[58:61], v[168:171], v[176:179], v[58:61]
	v_mfma_f32_16x16x32_bf16 v[54:57], v[160:163], v[186:189], v[54:57]
	v_mfma_f32_16x16x32_bf16 v[50:53], v[168:171], v[186:189], v[50:53]
	v_mfma_f32_16x16x32_bf16 v[30:33], v[160:163], v[194:197], v[30:33]
	v_mfma_f32_16x16x32_bf16 v[26:29], v[168:171], v[194:197], v[26:29]
	v_mfma_f32_16x16x32_bf16 v[22:25], v[160:163], v[202:205], v[22:25]
	v_mfma_f32_16x16x32_bf16 v[18:21], v[168:171], v[202:205], v[18:21]

	s_barrier
	s_add_i32 s74, s75, s71
	v_lshl_add_u64 v[148:149], v[228:229], 0, s[14:15]
	s_mov_b32 m0, s74
	s_nop 0
	global_load_lds_dwordx4 v[148:149], off
	v_lshl_add_u64 v[148:149], v[230:231], 0, s[14:15]
	s_add_i32 m0, s74, 0x2000
	s_nop 0
	global_load_lds_dwordx4 v[148:149], off
	s_waitcnt vmcnt(6)
	s_barrier

	v_mfma_f32_16x16x32_bf16 v[46:49], v[206:209], v[172:175], v[46:49]
	v_mfma_f32_16x16x32_bf16 v[42:45], v[214:217], v[172:175], v[42:45]
	v_mfma_f32_16x16x32_bf16 v[38:41], v[206:209], v[182:185], v[38:41]
	v_mfma_f32_16x16x32_bf16 v[34:37], v[214:217], v[182:185], v[34:37]
	v_mfma_f32_16x16x32_bf16 v[14:17], v[206:209], v[190:193], v[14:17]
	v_mfma_f32_16x16x32_bf16 v[10:13], v[214:217], v[190:193], v[10:13]
	v_mfma_f32_16x16x32_bf16 v[6:9], v[206:209], v[198:201], v[6:9]
	v_mfma_f32_16x16x32_bf16 v[2:5], v[214:217], v[198:201], v[2:5]
	v_mfma_f32_16x16x32_bf16 v[46:49], v[210:213], v[176:179], v[46:49]
	v_mfma_f32_16x16x32_bf16 v[42:45], v[218:221], v[176:179], v[42:45]
	v_mfma_f32_16x16x32_bf16 v[38:41], v[210:213], v[186:189], v[38:41]
	v_mfma_f32_16x16x32_bf16 v[34:37], v[218:221], v[186:189], v[34:37]
	v_mfma_f32_16x16x32_bf16 v[14:17], v[210:213], v[194:197], v[14:17]
	v_mfma_f32_16x16x32_bf16 v[10:13], v[218:221], v[194:197], v[10:13]
	v_mfma_f32_16x16x32_bf16 v[6:9], v[210:213], v[202:205], v[6:9]
	v_mfma_f32_16x16x32_bf16 v[2:5], v[218:221], v[202:205], v[2:5]

	s_add_u32 s78, s78, 0x100
	s_addc_u32 s79, s79, 0
	s_add_u32 s73, s73, 0x100
	s_addc_u32 vcc_lo, vcc_lo, 0
	s_cmp_ge_i32 vcc_hi, s91
	s_mov_b32 s80, vcc_hi
	s_barrier
	s_cbranch_scc0 .LBB0_102

.LBB0_259:
	s_or_b64 exec, exec, s[0:1]
	s_setprio 0
	s_add_u32 s26, s34, 0xb120000
	s_waitcnt lgkmcnt(0)
	v_mov_b32_e32 v1, v180
	s_addc_u32 s27, s35, 0
	s_barrier
	s_mov_b32 s0, 0
	v_writelane_b32 v242, s0, 57
	v_readfirstlane_b32 s0, v180
	s_nop 1
	s_cmpk_ge_u32 s0, 0x100
	s_cbranch_scc1 .Lp2_b

.Lprio_449:
	v_mov_b32_e32 v16, v180
	s_cmpk_lt_i32 s2, 0x200
	s_waitcnt lgkmcnt(0)
	s_barrier
	s_movk_i32 s0, 0x100
	v_readfirstlane_b32 s16, v16
	s_cselect_b64 s[96:97], -1, 0
	s_cmpk_gt_i32 s2, 0x1ff
	s_cbranch_scc1 .LBB0_478
	s_ashr_i32 s17, s2, 31
	s_lshr_b32 s1, s17, 29
	s_add_i32 s1, s2, s1
	s_and_b32 s3, s1, -8
	s_sub_i32 s6, s2, s3
	s_cmp_gt_i32 s6, -1
	s_cbranch_scc0 .LBB0_452
	s_lshl_b32 s3, s6, 6
	s_cbranch_execz .LBB0_453
	s_branch .LBB0_454

.LBB0_470:
	ds_read_b128 v[146:149], v160
	ds_read_b128 v[150:153], v160 offset:1024
	ds_read_b128 v[154:157], v160 offset:2048
	ds_read_b128 v[164:167], v160 offset:3072
	s_add_i32 s90, s62, 2
	s_add_u32 s72, s50, 0x80
	s_addc_u32 s63, s51, 0
	s_cmp_eq_u32 s78, s62
	s_cselect_b32 s62, s0, s72
	s_cselect_b32 s63, s1, s63
	s_cselect_b32 s73, s7, s89
	s_cselect_b32 s72, s6, s88
	v_lshl_add_u64 v[202:203], s[50:51], 0, v[138:139]
	s_add_i32 m0, s69, 0xc000
	ds_read_b128 v[168:171], v161
	ds_read_b128 v[172:175], v161 offset:1024
	ds_read_b128 v[176:179], v161 offset:2048
	ds_read_b128 v[182:185], v161 offset:3072
	ds_read_b128 v[186:189], v161 offset:4096
	ds_read_b128 v[190:193], v161 offset:5120
	ds_read_b128 v[194:197], v161 offset:6144
	ds_read_b128 v[198:201], v161 offset:7168
	global_load_lds_dwordx4 v[202:203], off
	v_lshl_add_u64 v[202:203], s[50:51], 0, v[140:141]
	s_add_i32 m0, s69, 0xe000
	s_nop 0
	global_load_lds_dwordx4 v[202:203], off
	s_waitcnt lgkmcnt(8)
	s_barrier
	s_waitcnt lgkmcnt(0)

	s_waitcnt lgkmcnt(0)
	v_mfma_f32_16x16x32_bf16 v[126:129], v[146:149], v[168:171], v[126:129]
	v_mfma_f32_16x16x32_bf16 v[122:125], v[154:157], v[168:171], v[122:125]
	v_mfma_f32_16x16x32_bf16 v[110:113], v[146:149], v[176:179], v[110:113]
	v_mfma_f32_16x16x32_bf16 v[106:109], v[154:157], v[176:179], v[106:109]
	v_mfma_f32_16x16x32_bf16 v[94:97], v[146:149], v[186:189], v[94:97]
	v_mfma_f32_16x16x32_bf16 v[90:93], v[154:157], v[186:189], v[90:93]
	v_mfma_f32_16x16x32_bf16 v[78:81], v[146:149], v[194:197], v[78:81]
	v_mfma_f32_16x16x32_bf16 v[74:77], v[154:157], v[194:197], v[74:77]
	v_mfma_f32_16x16x32_bf16 v[126:129], v[150:153], v[172:175], v[126:129]
	v_mfma_f32_16x16x32_bf16 v[122:125], v[164:167], v[172:175], v[122:125]
	v_mfma_f32_16x16x32_bf16 v[110:113], v[150:153], v[182:185], v[110:113]
	v_mfma_f32_16x16x32_bf16 v[106:109], v[164:167], v[182:185], v[106:109]
	v_mfma_f32_16x16x32_bf16 v[94:97], v[150:153], v[190:193], v[94:97]
	v_mfma_f32_16x16x32_bf16 v[90:93], v[164:167], v[190:193], v[90:93]
	v_mfma_f32_16x16x32_bf16 v[78:81], v[150:153], v[198:201], v[78:81]
	v_mfma_f32_16x16x32_bf16 v[74:77], v[164:167], v[198:201], v[74:77]

	s_barrier
	s_add_i32 s91, s81, s68
	v_lshl_add_u64 v[218:219], s[72:73], 0, v[132:133]
	s_mov_b32 m0, s91
	ds_read_b128 v[202:205], v162
	ds_read_b128 v[206:209], v162 offset:1024
	ds_read_b128 v[210:213], v162 offset:2048
	ds_read_b128 v[214:217], v162 offset:3072
	global_load_lds_dwordx4 v[218:219], off
	v_lshl_add_u64 v[220:221], s[72:73], 0, v[136:137]
	s_add_i32 m0, s91, 0x2000
	s_nop 0
	global_load_lds_dwordx4 v[220:221], off
	s_barrier
	s_waitcnt lgkmcnt(0)

	s_waitcnt lgkmcnt(0)
	v_mfma_f32_16x16x32_bf16 v[118:121], v[202:205], v[168:171], v[118:121]
	v_mfma_f32_16x16x32_bf16 v[114:117], v[210:213], v[168:171], v[114:117]
	v_mfma_f32_16x16x32_bf16 v[102:105], v[202:205], v[176:179], v[102:105]
	v_mfma_f32_16x16x32_bf16 v[98:101], v[210:213], v[176:179], v[98:101]
	v_mfma_f32_16x16x32_bf16 v[86:89], v[202:205], v[186:189], v[86:89]
	v_mfma_f32_16x16x32_bf16 v[82:85], v[210:213], v[186:189], v[82:85]
	v_mfma_f32_16x16x32_bf16 v[70:73], v[202:205], v[194:197], v[70:73]
	v_mfma_f32_16x16x32_bf16 v[66:69], v[210:213], v[194:197], v[66:69]
	v_mfma_f32_16x16x32_bf16 v[118:121], v[206:209], v[172:175], v[118:121]
	v_mfma_f32_16x16x32_bf16 v[114:117], v[214:217], v[172:175], v[114:117]
	v_mfma_f32_16x16x32_bf16 v[102:105], v[206:209], v[182:185], v[102:105]
	v_mfma_f32_16x16x32_bf16 v[98:101], v[214:217], v[182:185], v[98:101]
	v_mfma_f32_16x16x32_bf16 v[86:89], v[206:209], v[190:193], v[86:89]
	v_mfma_f32_16x16x32_bf16 v[82:85], v[214:217], v[190:193], v[82:85]
	v_mfma_f32_16x16x32_bf16 v[70:73], v[206:209], v[198:201], v[70:73]
	v_mfma_f32_16x16x32_bf16 v[66:69], v[214:217], v[198:201], v[66:69]

	s_mov_b32 m0, s69
	v_lshl_add_u64 v[222:223], s[62:63], 0, v[130:131]
	s_barrier
	ds_read_b128 v[168:171], v161 offset:16384
	ds_read_b128 v[172:175], v161 offset:17408
	ds_read_b128 v[176:179], v161 offset:18432
	ds_read_b128 v[182:185], v161 offset:19456
	ds_read_b128 v[186:189], v161 offset:20480
	ds_read_b128 v[190:193], v161 offset:21504
	ds_read_b128 v[194:197], v161 offset:22528
	ds_read_b128 v[198:201], v161 offset:23552
	global_load_lds_dwordx4 v[222:223], off
	v_lshl_add_u64 v[224:225], s[62:63], 0, v[134:135]
	s_mov_b32 m0, s70
	s_nop 0
	global_load_lds_dwordx4 v[224:225], off
	s_barrier
	s_waitcnt lgkmcnt(0)

	s_waitcnt lgkmcnt(0)
	v_mfma_f32_16x16x32_bf16 v[62:65], v[146:149], v[168:171], v[62:65]
	v_mfma_f32_16x16x32_bf16 v[58:61], v[154:157], v[168:171], v[58:61]
	v_mfma_f32_16x16x32_bf16 v[46:49], v[146:149], v[176:179], v[46:49]
	v_mfma_f32_16x16x32_bf16 v[42:45], v[154:157], v[176:179], v[42:45]
	v_mfma_f32_16x16x32_bf16 v[30:33], v[146:149], v[186:189], v[30:33]
	v_mfma_f32_16x16x32_bf16 v[26:29], v[154:157], v[186:189], v[26:29]
	v_mfma_f32_16x16x32_bf16 v[14:17], v[146:149], v[194:197], v[14:17]
	v_mfma_f32_16x16x32_bf16 v[10:13], v[154:157], v[194:197], v[10:13]
	v_mfma_f32_16x16x32_bf16 v[62:65], v[150:153], v[172:175], v[62:65]
	v_mfma_f32_16x16x32_bf16 v[58:61], v[164:167], v[172:175], v[58:61]
	v_mfma_f32_16x16x32_bf16 v[46:49], v[150:153], v[182:185], v[46:49]
	v_mfma_f32_16x16x32_bf16 v[42:45], v[164:167], v[182:185], v[42:45]
	v_mfma_f32_16x16x32_bf16 v[30:33], v[150:153], v[190:193], v[30:33]
	v_mfma_f32_16x16x32_bf16 v[26:29], v[164:167], v[190:193], v[26:29]
	v_mfma_f32_16x16x32_bf16 v[14:17], v[150:153], v[198:201], v[14:17]
	v_mfma_f32_16x16x32_bf16 v[10:13], v[164:167], v[198:201], v[10:13]

	s_barrier
	s_add_u32 s72, s72, s10
	s_addc_u32 s73, s73, s11
	s_add_i32 s91, s82, s68
	v_lshl_add_u64 v[226:227], s[72:73], 0, v[132:133]
	s_mov_b32 m0, s91
	v_lshl_add_u64 v[228:229], s[72:73], 0, v[136:137]
	global_load_lds_dwordx4 v[226:227], off
	s_add_i32 m0, s91, 0x2000
	s_nop 0
	global_load_lds_dwordx4 v[228:229], off
	s_waitcnt vmcnt(6)
	s_barrier

	v_mfma_f32_16x16x32_bf16 v[54:57], v[202:205], v[168:171], v[54:57]
	v_mfma_f32_16x16x32_bf16 v[50:53], v[210:213], v[168:171], v[50:53]
	v_mfma_f32_16x16x32_bf16 v[38:41], v[202:205], v[176:179], v[38:41]
	v_mfma_f32_16x16x32_bf16 v[34:37], v[210:213], v[176:179], v[34:37]
	v_mfma_f32_16x16x32_bf16 v[22:25], v[202:205], v[186:189], v[22:25]
	v_mfma_f32_16x16x32_bf16 v[18:21], v[210:213], v[186:189], v[18:21]
	v_mfma_f32_16x16x32_bf16 v[6:9], v[202:205], v[194:197], v[6:9]
	v_mfma_f32_16x16x32_bf16 v[2:5], v[210:213], v[194:197], v[2:5]
	v_mfma_f32_16x16x32_bf16 v[54:57], v[206:209], v[172:175], v[54:57]
	v_mfma_f32_16x16x32_bf16 v[50:53], v[214:217], v[172:175], v[50:53]
	v_mfma_f32_16x16x32_bf16 v[38:41], v[206:209], v[182:185], v[38:41]
	v_mfma_f32_16x16x32_bf16 v[34:37], v[214:217], v[182:185], v[34:37]
	v_mfma_f32_16x16x32_bf16 v[22:25], v[206:209], v[190:193], v[22:25]
	v_mfma_f32_16x16x32_bf16 v[18:21], v[214:217], v[190:193], v[18:21]
	v_mfma_f32_16x16x32_bf16 v[6:9], v[206:209], v[198:201], v[6:9]
	v_mfma_f32_16x16x32_bf16 v[2:5], v[214:217], v[198:201], v[2:5]

	s_add_i32 s72, 0, 0x18000
	v_add_u32_e32 v163, s72, v158
	s_barrier
	ds_read_b128 v[146:149], v163
	ds_read_b128 v[150:153], v163 offset:1024
	ds_read_b128 v[154:157], v163 offset:2048
	ds_read_b128 v[164:167], v163 offset:3072
	s_add_u32 s62, s62, s10
	s_addc_u32 s63, s63, s11
	s_mov_b32 m0, s3
	v_lshl_add_u64 v[202:203], s[62:63], 0, v[130:131]
	ds_read_b128 v[168:171], v161 offset:32768
	ds_read_b128 v[172:175], v161 offset:33792
	ds_read_b128 v[176:179], v161 offset:34816
	ds_read_b128 v[182:185], v161 offset:35840
	ds_read_b128 v[186:189], v161 offset:36864
	ds_read_b128 v[190:193], v161 offset:37888
	ds_read_b128 v[194:197], v161 offset:38912
	ds_read_b128 v[198:201], v161 offset:39936
	global_load_lds_dwordx4 v[202:203], off
	v_lshl_add_u64 v[202:203], s[62:63], 0, v[134:135]
	s_mov_b32 m0, s71
	s_nop 0
	global_load_lds_dwordx4 v[202:203], off
	s_waitcnt lgkmcnt(8)
	s_barrier
	s_waitcnt lgkmcnt(0)

	s_waitcnt lgkmcnt(0)
	v_mfma_f32_16x16x32_bf16 v[126:129], v[146:149], v[168:171], v[126:129]
	v_mfma_f32_16x16x32_bf16 v[122:125], v[154:157], v[168:171], v[122:125]
	v_mfma_f32_16x16x32_bf16 v[110:113], v[146:149], v[176:179], v[110:113]
	v_mfma_f32_16x16x32_bf16 v[106:109], v[154:157], v[176:179], v[106:109]
	v_mfma_f32_16x16x32_bf16 v[94:97], v[146:149], v[186:189], v[94:97]
	v_mfma_f32_16x16x32_bf16 v[90:93], v[154:157], v[186:189], v[90:93]
	v_mfma_f32_16x16x32_bf16 v[78:81], v[146:149], v[194:197], v[78:81]
	v_mfma_f32_16x16x32_bf16 v[74:77], v[154:157], v[194:197], v[74:77]
	v_mfma_f32_16x16x32_bf16 v[126:129], v[150:153], v[172:175], v[126:129]
	v_mfma_f32_16x16x32_bf16 v[122:125], v[164:167], v[172:175], v[122:125]
	v_mfma_f32_16x16x32_bf16 v[110:113], v[150:153], v[182:185], v[110:113]
	v_mfma_f32_16x16x32_bf16 v[106:109], v[164:167], v[182:185], v[106:109]
	v_mfma_f32_16x16x32_bf16 v[94:97], v[150:153], v[190:193], v[94:97]
	v_mfma_f32_16x16x32_bf16 v[90:93], v[164:167], v[190:193], v[90:93]
	v_mfma_f32_16x16x32_bf16 v[78:81], v[150:153], v[198:201], v[78:81]
	v_mfma_f32_16x16x32_bf16 v[74:77], v[164:167], v[198:201], v[74:77]

	s_barrier
	s_add_i32 s62, 0, 0x1c000
	s_add_i32 s63, s72, s68
	v_add_u32_e32 v163, s62, v158
	v_lshl_add_u64 v[218:219], v[218:219], 0, s[14:15]
	s_mov_b32 m0, s63
	ds_read_b128 v[202:205], v163
	ds_read_b128 v[206:209], v163 offset:1024
	ds_read_b128 v[210:213], v163 offset:2048
	ds_read_b128 v[214:217], v163 offset:3072
	global_load_lds_dwordx4 v[218:219], off
	v_lshl_add_u64 v[218:219], v[220:221], 0, s[14:15]
	s_add_i32 m0, s63, 0x2000
	s_nop 0
	global_load_lds_dwordx4 v[218:219], off
	s_barrier
	s_waitcnt lgkmcnt(0)

	s_waitcnt lgkmcnt(0)
	v_mfma_f32_16x16x32_bf16 v[118:121], v[202:205], v[168:171], v[118:121]
	v_mfma_f32_16x16x32_bf16 v[114:117], v[210:213], v[168:171], v[114:117]
	v_mfma_f32_16x16x32_bf16 v[102:105], v[202:205], v[176:179], v[102:105]
	v_mfma_f32_16x16x32_bf16 v[98:101], v[210:213], v[176:179], v[98:101]
	v_mfma_f32_16x16x32_bf16 v[86:89], v[202:205], v[186:189], v[86:89]
	v_mfma_f32_16x16x32_bf16 v[82:85], v[210:213], v[186:189], v[82:85]
	v_mfma_f32_16x16x32_bf16 v[70:73], v[202:205], v[194:197], v[70:73]
	v_mfma_f32_16x16x32_bf16 v[66:69], v[210:213], v[194:197], v[66:69]
	v_mfma_f32_16x16x32_bf16 v[118:121], v[206:209], v[172:175], v[118:121]
	v_mfma_f32_16x16x32_bf16 v[114:117], v[214:217], v[172:175], v[114:117]
	v_mfma_f32_16x16x32_bf16 v[102:105], v[206:209], v[182:185], v[102:105]
	v_mfma_f32_16x16x32_bf16 v[98:101], v[214:217], v[182:185], v[98:101]
	v_mfma_f32_16x16x32_bf16 v[86:89], v[206:209], v[190:193], v[86:89]
	v_mfma_f32_16x16x32_bf16 v[82:85], v[214:217], v[190:193], v[82:85]
	v_mfma_f32_16x16x32_bf16 v[70:73], v[206:209], v[198:201], v[70:73]
	v_mfma_f32_16x16x32_bf16 v[66:69], v[214:217], v[198:201], v[66:69]

	s_mov_b32 m0, s75
	v_lshl_add_u64 v[218:219], v[222:223], 0, s[14:15]
	s_barrier
	ds_read_b128 v[168:171], v161 offset:49152
	ds_read_b128 v[172:175], v161 offset:50176
	ds_read_b128 v[176:179], v161 offset:51200
	ds_read_b128 v[182:185], v161 offset:52224
	ds_read_b128 v[186:189], v161 offset:53248
	ds_read_b128 v[190:193], v161 offset:54272
	ds_read_b128 v[194:197], v161 offset:55296
	ds_read_b128 v[198:201], v161 offset:56320
	global_load_lds_dwordx4 v[218:219], off
	v_lshl_add_u64 v[218:219], v[224:225], 0, s[14:15]
	s_mov_b32 m0, s76
	s_nop 0
	global_load_lds_dwordx4 v[218:219], off
	s_barrier
	s_waitcnt lgkmcnt(0)

	s_waitcnt lgkmcnt(0)
	v_mfma_f32_16x16x32_bf16 v[62:65], v[146:149], v[168:171], v[62:65]
	v_mfma_f32_16x16x32_bf16 v[58:61], v[154:157], v[168:171], v[58:61]
	v_mfma_f32_16x16x32_bf16 v[46:49], v[146:149], v[176:179], v[46:49]
	v_mfma_f32_16x16x32_bf16 v[42:45], v[154:157], v[176:179], v[42:45]
	v_mfma_f32_16x16x32_bf16 v[30:33], v[146:149], v[186:189], v[30:33]
	v_mfma_f32_16x16x32_bf16 v[26:29], v[154:157], v[186:189], v[26:29]
	v_mfma_f32_16x16x32_bf16 v[14:17], v[146:149], v[194:197], v[14:17]
	v_mfma_f32_16x16x32_bf16 v[10:13], v[154:157], v[194:197], v[10:13]
	v_mfma_f32_16x16x32_bf16 v[62:65], v[150:153], v[172:175], v[62:65]
	v_mfma_f32_16x16x32_bf16 v[58:61], v[164:167], v[172:175], v[58:61]
	v_mfma_f32_16x16x32_bf16 v[46:49], v[150:153], v[182:185], v[46:49]
	v_mfma_f32_16x16x32_bf16 v[42:45], v[164:167], v[182:185], v[42:45]
	v_mfma_f32_16x16x32_bf16 v[30:33], v[150:153], v[190:193], v[30:33]
	v_mfma_f32_16x16x32_bf16 v[26:29], v[164:167], v[190:193], v[26:29]
	v_mfma_f32_16x16x32_bf16 v[14:17], v[150:153], v[198:201], v[14:17]
	v_mfma_f32_16x16x32_bf16 v[10:13], v[164:167], v[198:201], v[10:13]

	s_barrier
	s_add_i32 s62, s62, s68
	v_lshl_add_u64 v[146:147], v[226:227], 0, s[14:15]
	s_mov_b32 m0, s62
	s_nop 0
	global_load_lds_dwordx4 v[146:147], off
	v_lshl_add_u64 v[146:147], v[228:229], 0, s[14:15]
	s_add_i32 m0, s62, 0x2000
	s_nop 0
	global_load_lds_dwordx4 v[146:147], off
	s_waitcnt vmcnt(6)
	s_barrier

	v_mfma_f32_16x16x32_bf16 v[54:57], v[202:205], v[168:171], v[54:57]
	v_mfma_f32_16x16x32_bf16 v[50:53], v[210:213], v[168:171], v[50:53]
	v_mfma_f32_16x16x32_bf16 v[38:41], v[202:205], v[176:179], v[38:41]
	v_mfma_f32_16x16x32_bf16 v[34:37], v[210:213], v[176:179], v[34:37]
	v_mfma_f32_16x16x32_bf16 v[22:25], v[202:205], v[186:189], v[22:25]
	v_mfma_f32_16x16x32_bf16 v[18:21], v[210:213], v[186:189], v[18:21]
	v_mfma_f32_16x16x32_bf16 v[6:9], v[202:205], v[194:197], v[6:9]
	v_mfma_f32_16x16x32_bf16 v[2:5], v[210:213], v[194:197], v[2:5]
	v_mfma_f32_16x16x32_bf16 v[54:57], v[206:209], v[172:175], v[54:57]
	v_mfma_f32_16x16x32_bf16 v[50:53], v[214:217], v[172:175], v[50:53]
	v_mfma_f32_16x16x32_bf16 v[38:41], v[206:209], v[182:185], v[38:41]
	v_mfma_f32_16x16x32_bf16 v[34:37], v[214:217], v[182:185], v[34:37]
	v_mfma_f32_16x16x32_bf16 v[22:25], v[206:209], v[190:193], v[22:25]
	v_mfma_f32_16x16x32_bf16 v[18:21], v[214:217], v[190:193], v[18:21]
	v_mfma_f32_16x16x32_bf16 v[6:9], v[206:209], v[198:201], v[6:9]
	v_mfma_f32_16x16x32_bf16 v[2:5], v[214:217], v[198:201], v[2:5]

	s_add_u32 s50, s50, 0x100
	s_addc_u32 s51, s51, 0
	s_add_u32 s88, s88, 0x100
	s_addc_u32 s89, s89, 0
	s_cmp_ge_i32 s90, s77
	s_mov_b32 s62, s90
	s_barrier
	s_cbranch_scc0 .LBB0_470

.LBB0_530:
	s_or_b64 exec, exec, s[0:1]
	s_setprio 0
	s_cmpk_gt_i32 s2, 0xff
	v_mbcnt_lo_u32_b32 v181, -1, 0
	s_waitcnt lgkmcnt(0)
	s_barrier
	s_cbranch_scc1 .LBB0_590
	s_add_u32 s75, s34, 0x10220000
	s_addc_u32 s79, s35, 0
	s_add_u32 s46, s34, 0x5120000
	s_addc_u32 s47, s35, 0
	s_add_u32 s50, s34, 0xc220000
	s_addc_u32 s51, s35, 0
	v_writelane_b32 v242, s96, 15
	s_add_u32 s62, s34, 0x17220000
	s_mov_b32 s69, s95
	v_writelane_b32 v242, s97, 16
	s_addc_u32 s63, s35, 0
	s_mov_b32 s73, 0
	s_add_i32 s82, 0, 0x14800
	v_mov_b32_e32 v94, 0
	s_movk_i32 s83, 0xc00
	s_mov_b32 s74, 0x3db504f3
	s_movk_i32 s84, 0x210
	s_add_i32 s85, 0, 0x10800
	v_mov_b32_e32 v118, 0x3ecc95a3
	s_add_i32 s86, 0, 0x8400
	s_movk_i32 s87, 0x220
	s_movk_i32 s88, 0x1000
	s_add_i32 s89, 0, 0x1e000
	s_add_i32 s90, 0, 0x15800
	s_mov_b64 s[76:77], 0xc00
	s_mov_b32 s91, 0x800000
	s_add_i32 s92, 0, 0x11000
	s_add_i32 s93, 0, 0x4400
	s_movk_i32 s94, 0x110
	s_add_i32 s95, 0, 0x8800
	s_add_i32 s96, 0, 0x1f800
	s_mov_b32 s78, 0x3c800000
	s_movk_i32 s97, 0x7fff
	v_mov_b32_e32 v119, 0x7f800000
	v_mov_b32_e32 v120, 0x7fc00000
	v_mov_b32_e32 v121, 0xff800000
	v_mbcnt_hi_u32_b32 v122, -1, v181
	v_mov_b32_e32 v123, 0x100
	s_mov_b32 s71, s2
	s_branch .LBB0_533

.Lgs_659:
.LBB0_600:
	s_or_b64 exec, exec, s[0:1]
	s_setprio 0
	s_waitcnt lgkmcnt(0)
	s_mul_i32 s14, s18, 24
	v_mov_b32_e32 v9, v180
	s_barrier
	s_mov_b32 s3, 0x8000
	v_ashrrev_i32_e32 v0, 6, v9
	v_add_u32_e32 v8, s95, v0
	v_cmp_gt_i32_e32 vcc, s3, v8
	s_and_saveexec_b64 s[0:1], vcc
	s_cbranch_execz .LBB0_607
	v_lshlrev_b32_e32 v0, 5, v9
	s_waitcnt vmcnt(4)
	v_and_b32_e32 v10, 0x1e0, v0
	global_load_dwordx4 v[0:3], v10, s[20:21]
	global_load_dwordx4 v[4:7], v10, s[20:21] offset:16
	v_lshlrev_b32_e32 v9, 3, v9
	v_and_b32_e32 v9, 0x1f8, v9
	v_lshlrev_b32_e32 v10, 2, v9
	v_mov_b32_e32 v11, 0
	v_lshl_add_u64 v[12:13], s[34:35], 0, v[10:11]
	s_mov_b64 s[4:5], 0x10220000
	v_lshlrev_b32_e32 v10, 1, v9
	v_lshl_add_u64 v[44:45], v[12:13], 0, s[4:5]
	v_lshl_add_u64 v[10:11], s[34:35], 0, v[10:11]
	s_mov_b64 s[4:5], 0x14220000
	v_lshl_add_u64 v[46:47], v[10:11], 0, s[4:5]
	s_mov_b64 s[4:5], 0x17220000
	s_add_i32 s11, s33, s33
	v_lshl_add_u64 v[48:49], v[10:11], 0, s[4:5]
	s_lshl_b32 s8, s18, 4
	s_mov_b64 s[4:5], 0
	s_movk_i32 s9, 0x7fff
	v_mov_b32_e32 v56, 0x358637bd
	s_mov_b32 s10, 0x800000
	s_add_i32 s11, s11, s33
	s_branch .LBB0_603

.Lprio_659:
	v_mov_b32_e32 v1, v180
	s_waitcnt lgkmcnt(0)
	v_cndmask_b32_e64 v0, 0, 1, s[96:97]
	s_barrier
	s_movk_i32 s0, 0x400
	v_readfirstlane_b32 s16, v1
	v_cmp_ne_u32_e64 s[4:5], 1, v0
	s_andn2_b64 vcc, exec, s[96:97]
	s_cbranch_vccnz .LBB0_691
	s_ashr_i32 s17, s2, 31
	s_lshr_b32 s1, s17, 29
	s_add_i32 s1, s2, s1
	s_and_b32 s3, s1, -8
	s_sub_i32 s3, s2, s3
	s_cmp_gt_i32 s3, -1
	s_cbranch_scc0 .LBB0_662
	s_lshl_b32 s12, s3, 6
	s_cbranch_execz .LBB0_663
	s_branch .LBB0_664

.LBB0_678:
	s_add_i32 s68, s68, 2
	s_and_b64 s[64:65], exec, s[64:65]
	s_cselect_b32 s65, s53, s97
	s_cselect_b32 s64, s52, s96
	s_add_i32 s3, 0, 0x10000
	v_add_u32_e32 v1, s3, v196
	ds_read_b128 v[132:135], v1
	ds_read_b128 v[136:139], v1 offset:1024
	ds_read_b128 v[140:143], v1 offset:2048
	ds_read_b128 v[144:147], v1 offset:3072
	s_add_u32 s62, s62, 0x20000
	s_addc_u32 s63, s63, 0
	v_lshl_add_u64 v[2:3], s[62:63], 0, v[182:183]
	s_add_i32 m0, s70, 0xc000
	ds_read_b128 v[148:151], v197
	ds_read_b128 v[152:155], v197 offset:1024
	ds_read_b128 v[156:159], v197 offset:2048
	ds_read_b128 v[160:163], v197 offset:3072
	ds_read_b128 v[164:167], v197 offset:4096
	ds_read_b128 v[168:171], v197 offset:5120
	ds_read_b128 v[172:175], v197 offset:6144
	ds_read_b128 v[176:179], v197 offset:7168
	global_load_lds_dwordx4 v[2:3], off
	v_lshl_add_u64 v[2:3], s[62:63], 0, v[186:187]
	s_add_i32 m0, s70, 0xe000
	s_nop 0
	global_load_lds_dwordx4 v[2:3], off
	s_waitcnt lgkmcnt(8)
	s_barrier
	s_waitcnt lgkmcnt(0)

	s_waitcnt lgkmcnt(0)
	v_mfma_f32_16x16x32_bf16 v[124:127], v[132:135], v[148:151], v[124:127]
	v_mfma_f32_16x16x32_bf16 v[128:131], v[140:143], v[148:151], v[128:131]
	v_mfma_f32_16x16x32_bf16 v[108:111], v[132:135], v[156:159], v[108:111]
	v_mfma_f32_16x16x32_bf16 v[112:115], v[140:143], v[156:159], v[112:115]
	v_mfma_f32_16x16x32_bf16 v[92:95], v[132:135], v[164:167], v[92:95]
	v_mfma_f32_16x16x32_bf16 v[96:99], v[140:143], v[164:167], v[96:99]
	v_mfma_f32_16x16x32_bf16 v[76:79], v[132:135], v[172:175], v[76:79]
	v_mfma_f32_16x16x32_bf16 v[80:83], v[140:143], v[172:175], v[80:83]
	v_mfma_f32_16x16x32_bf16 v[124:127], v[136:139], v[152:155], v[124:127]
	v_mfma_f32_16x16x32_bf16 v[128:131], v[144:147], v[152:155], v[128:131]
	v_mfma_f32_16x16x32_bf16 v[108:111], v[136:139], v[160:163], v[108:111]
	v_mfma_f32_16x16x32_bf16 v[112:115], v[144:147], v[160:163], v[112:115]
	v_mfma_f32_16x16x32_bf16 v[92:95], v[136:139], v[168:171], v[92:95]
	v_mfma_f32_16x16x32_bf16 v[96:99], v[144:147], v[168:171], v[96:99]
	v_mfma_f32_16x16x32_bf16 v[76:79], v[136:139], v[176:179], v[76:79]
	v_mfma_f32_16x16x32_bf16 v[80:83], v[144:147], v[176:179], v[80:83]

	s_barrier
	s_add_i32 s3, s3, s67
	v_add_u32_e32 v1, s90, v196
	v_lshl_add_u64 v[214:215], s[64:65], 0, v[184:185]
	s_mov_b32 m0, s3
	ds_read_b128 v[198:201], v1
	ds_read_b128 v[202:205], v1 offset:1024
	ds_read_b128 v[206:209], v1 offset:2048
	ds_read_b128 v[210:213], v1 offset:3072
	global_load_lds_dwordx4 v[214:215], off
	v_lshl_add_u64 v[216:217], s[64:65], 0, v[188:189]
	s_add_i32 m0, s3, 0x2000
	s_nop 0
	global_load_lds_dwordx4 v[216:217], off
	s_barrier
	s_waitcnt lgkmcnt(0)

	s_waitcnt lgkmcnt(0)
	v_mfma_f32_16x16x32_bf16 v[116:119], v[198:201], v[148:151], v[116:119]
	v_mfma_f32_16x16x32_bf16 v[120:123], v[206:209], v[148:151], v[120:123]
	v_mfma_f32_16x16x32_bf16 v[100:103], v[198:201], v[156:159], v[100:103]
	v_mfma_f32_16x16x32_bf16 v[104:107], v[206:209], v[156:159], v[104:107]
	v_mfma_f32_16x16x32_bf16 v[84:87], v[198:201], v[164:167], v[84:87]
	v_mfma_f32_16x16x32_bf16 v[88:91], v[206:209], v[164:167], v[88:91]
	v_mfma_f32_16x16x32_bf16 v[68:71], v[198:201], v[172:175], v[68:71]
	v_mfma_f32_16x16x32_bf16 v[72:75], v[206:209], v[172:175], v[72:75]
	v_mfma_f32_16x16x32_bf16 v[116:119], v[202:205], v[152:155], v[116:119]
	v_mfma_f32_16x16x32_bf16 v[120:123], v[210:213], v[152:155], v[120:123]
	v_mfma_f32_16x16x32_bf16 v[100:103], v[202:205], v[160:163], v[100:103]
	v_mfma_f32_16x16x32_bf16 v[104:107], v[210:213], v[160:163], v[104:107]
	v_mfma_f32_16x16x32_bf16 v[84:87], v[202:205], v[168:171], v[84:87]
	v_mfma_f32_16x16x32_bf16 v[88:91], v[210:213], v[168:171], v[88:91]
	v_mfma_f32_16x16x32_bf16 v[68:71], v[202:205], v[176:179], v[68:71]
	v_mfma_f32_16x16x32_bf16 v[72:75], v[210:213], v[176:179], v[72:75]

	s_mov_b32 m0, s70
	v_lshl_add_u64 v[218:219], s[60:61], 0, v[182:183]
	s_barrier
	ds_read_b128 v[148:151], v197 offset:16384
	ds_read_b128 v[152:155], v197 offset:17408
	ds_read_b128 v[156:159], v197 offset:18432
	ds_read_b128 v[160:163], v197 offset:19456
	ds_read_b128 v[164:167], v197 offset:20480
	ds_read_b128 v[168:171], v197 offset:21504
	ds_read_b128 v[172:175], v197 offset:22528
	ds_read_b128 v[176:179], v197 offset:23552
	global_load_lds_dwordx4 v[218:219], off
	v_lshl_add_u64 v[220:221], s[60:61], 0, v[186:187]
	s_mov_b32 m0, s71
	s_nop 0
	global_load_lds_dwordx4 v[220:221], off
	s_barrier
	s_waitcnt lgkmcnt(0)

	s_waitcnt lgkmcnt(0)
	v_mfma_f32_16x16x32_bf16 v[60:63], v[132:135], v[148:151], v[60:63]
	v_mfma_f32_16x16x32_bf16 v[64:67], v[140:143], v[148:151], v[64:67]
	v_mfma_f32_16x16x32_bf16 v[44:47], v[132:135], v[156:159], v[44:47]
	v_mfma_f32_16x16x32_bf16 v[48:51], v[140:143], v[156:159], v[48:51]
	v_mfma_f32_16x16x32_bf16 v[28:31], v[132:135], v[164:167], v[28:31]
	v_mfma_f32_16x16x32_bf16 v[32:35], v[140:143], v[164:167], v[32:35]
	v_mfma_f32_16x16x32_bf16 v[12:15], v[132:135], v[172:175], v[12:15]
	v_mfma_f32_16x16x32_bf16 v[16:19], v[140:143], v[172:175], v[16:19]
	v_mfma_f32_16x16x32_bf16 v[60:63], v[136:139], v[152:155], v[60:63]
	v_mfma_f32_16x16x32_bf16 v[64:67], v[144:147], v[152:155], v[64:67]
	v_mfma_f32_16x16x32_bf16 v[44:47], v[136:139], v[160:163], v[44:47]
	v_mfma_f32_16x16x32_bf16 v[48:51], v[144:147], v[160:163], v[48:51]
	v_mfma_f32_16x16x32_bf16 v[28:31], v[136:139], v[168:171], v[28:31]
	v_mfma_f32_16x16x32_bf16 v[32:35], v[144:147], v[168:171], v[32:35]
	v_mfma_f32_16x16x32_bf16 v[12:15], v[136:139], v[176:179], v[12:15]
	v_mfma_f32_16x16x32_bf16 v[16:19], v[144:147], v[176:179], v[16:19]

	s_barrier
	s_add_u32 s62, s64, s8
	s_addc_u32 s63, s65, s9
	s_add_i32 s3, s90, s67
	v_lshl_add_u64 v[222:223], s[62:63], 0, v[184:185]
	s_mov_b32 m0, s3
	v_lshl_add_u64 v[224:225], s[62:63], 0, v[188:189]
	global_load_lds_dwordx4 v[222:223], off
	s_add_i32 m0, s3, 0x2000
	s_nop 0
	global_load_lds_dwordx4 v[224:225], off
	s_waitcnt vmcnt(6)
	s_barrier

	v_mfma_f32_16x16x32_bf16 v[52:55], v[198:201], v[148:151], v[52:55]
	v_mfma_f32_16x16x32_bf16 v[56:59], v[206:209], v[148:151], v[56:59]
	v_mfma_f32_16x16x32_bf16 v[36:39], v[198:201], v[156:159], v[36:39]
	v_mfma_f32_16x16x32_bf16 v[40:43], v[206:209], v[156:159], v[40:43]
	v_mfma_f32_16x16x32_bf16 v[20:23], v[198:201], v[164:167], v[20:23]
	v_mfma_f32_16x16x32_bf16 v[24:27], v[206:209], v[164:167], v[24:27]
	v_mfma_f32_16x16x32_bf16 v[2:5], v[198:201], v[172:175], v[4:7]
	v_mfma_f32_16x16x32_bf16 v[6:9], v[206:209], v[172:175], v[8:11]
	v_mfma_f32_16x16x32_bf16 v[52:55], v[202:205], v[152:155], v[52:55]
	v_mfma_f32_16x16x32_bf16 v[56:59], v[210:213], v[152:155], v[56:59]
	v_mfma_f32_16x16x32_bf16 v[36:39], v[202:205], v[160:163], v[36:39]
	v_mfma_f32_16x16x32_bf16 v[40:43], v[210:213], v[160:163], v[40:43]
	v_mfma_f32_16x16x32_bf16 v[20:23], v[202:205], v[168:171], v[20:23]
	v_mfma_f32_16x16x32_bf16 v[24:27], v[210:213], v[168:171], v[24:27]
	v_mfma_f32_16x16x32_bf16 v[2:5], v[202:205], v[176:179], v[2:5]
	v_mfma_f32_16x16x32_bf16 v[8:11], v[210:213], v[176:179], v[6:9]

	s_add_i32 s3, 0, 0x18000
	v_add_u32_e32 v1, s3, v196
	s_barrier
	ds_read_b128 v[132:135], v1
	ds_read_b128 v[136:139], v1 offset:1024
	ds_read_b128 v[140:143], v1 offset:2048
	ds_read_b128 v[144:147], v1 offset:3072
	s_add_u32 s60, s60, 0x20000
	s_addc_u32 s61, s61, 0
	s_mov_b32 m0, s72
	v_lshl_add_u64 v[6:7], s[60:61], 0, v[182:183]
	ds_read_b128 v[148:151], v197 offset:32768
	ds_read_b128 v[152:155], v197 offset:33792
	ds_read_b128 v[156:159], v197 offset:34816
	ds_read_b128 v[160:163], v197 offset:35840
	ds_read_b128 v[164:167], v197 offset:36864
	ds_read_b128 v[168:171], v197 offset:37888
	ds_read_b128 v[172:175], v197 offset:38912
	ds_read_b128 v[176:179], v197 offset:39936
	global_load_lds_dwordx4 v[6:7], off
	v_lshl_add_u64 v[6:7], s[60:61], 0, v[186:187]
	s_mov_b32 m0, s73
	s_nop 0
	global_load_lds_dwordx4 v[6:7], off
	s_waitcnt lgkmcnt(8)
	s_barrier
	s_waitcnt lgkmcnt(0)

	s_waitcnt lgkmcnt(0)
	v_mfma_f32_16x16x32_bf16 v[124:127], v[132:135], v[148:151], v[124:127]
	v_mfma_f32_16x16x32_bf16 v[128:131], v[140:143], v[148:151], v[128:131]
	v_mfma_f32_16x16x32_bf16 v[108:111], v[132:135], v[156:159], v[108:111]
	v_mfma_f32_16x16x32_bf16 v[112:115], v[140:143], v[156:159], v[112:115]
	v_mfma_f32_16x16x32_bf16 v[92:95], v[132:135], v[164:167], v[92:95]
	v_mfma_f32_16x16x32_bf16 v[96:99], v[140:143], v[164:167], v[96:99]
	v_mfma_f32_16x16x32_bf16 v[76:79], v[132:135], v[172:175], v[76:79]
	v_mfma_f32_16x16x32_bf16 v[80:83], v[140:143], v[172:175], v[80:83]
	v_mfma_f32_16x16x32_bf16 v[124:127], v[136:139], v[152:155], v[124:127]
	v_mfma_f32_16x16x32_bf16 v[128:131], v[144:147], v[152:155], v[128:131]
	v_mfma_f32_16x16x32_bf16 v[108:111], v[136:139], v[160:163], v[108:111]
	v_mfma_f32_16x16x32_bf16 v[112:115], v[144:147], v[160:163], v[112:115]
	v_mfma_f32_16x16x32_bf16 v[92:95], v[136:139], v[168:171], v[92:95]
	v_mfma_f32_16x16x32_bf16 v[96:99], v[144:147], v[168:171], v[96:99]
	v_mfma_f32_16x16x32_bf16 v[76:79], v[136:139], v[176:179], v[76:79]
	v_mfma_f32_16x16x32_bf16 v[80:83], v[144:147], v[176:179], v[80:83]

	s_barrier
	s_add_i32 s12, 0, 0x1c000
	s_add_i32 s3, s3, s67
	v_add_u32_e32 v1, s12, v196
	v_lshl_add_u64 v[6:7], v[214:215], 0, s[14:15]
	s_mov_b32 m0, s3
	ds_read_b128 v[198:201], v1
	ds_read_b128 v[202:205], v1 offset:1024
	ds_read_b128 v[206:209], v1 offset:2048
	ds_read_b128 v[210:213], v1 offset:3072
	global_load_lds_dwordx4 v[6:7], off
	v_lshl_add_u64 v[6:7], v[216:217], 0, s[14:15]
	s_add_i32 m0, s3, 0x2000
	s_nop 0
	global_load_lds_dwordx4 v[6:7], off
	s_barrier
	s_waitcnt lgkmcnt(0)

	s_waitcnt lgkmcnt(0)
	v_mfma_f32_16x16x32_bf16 v[116:119], v[198:201], v[148:151], v[116:119]
	v_mfma_f32_16x16x32_bf16 v[120:123], v[206:209], v[148:151], v[120:123]
	v_mfma_f32_16x16x32_bf16 v[100:103], v[198:201], v[156:159], v[100:103]
	v_mfma_f32_16x16x32_bf16 v[104:107], v[206:209], v[156:159], v[104:107]
	v_mfma_f32_16x16x32_bf16 v[84:87], v[198:201], v[164:167], v[84:87]
	v_mfma_f32_16x16x32_bf16 v[88:91], v[206:209], v[164:167], v[88:91]
	v_mfma_f32_16x16x32_bf16 v[68:71], v[198:201], v[172:175], v[68:71]
	v_mfma_f32_16x16x32_bf16 v[72:75], v[206:209], v[172:175], v[72:75]
	v_mfma_f32_16x16x32_bf16 v[116:119], v[202:205], v[152:155], v[116:119]
	v_mfma_f32_16x16x32_bf16 v[120:123], v[210:213], v[152:155], v[120:123]
	v_mfma_f32_16x16x32_bf16 v[100:103], v[202:205], v[160:163], v[100:103]
	v_mfma_f32_16x16x32_bf16 v[104:107], v[210:213], v[160:163], v[104:107]
	v_mfma_f32_16x16x32_bf16 v[84:87], v[202:205], v[168:171], v[84:87]
	v_mfma_f32_16x16x32_bf16 v[88:91], v[210:213], v[168:171], v[88:91]
	v_mfma_f32_16x16x32_bf16 v[68:71], v[202:205], v[176:179], v[68:71]
	v_mfma_f32_16x16x32_bf16 v[72:75], v[210:213], v[176:179], v[72:75]

	s_mov_b32 m0, s76
	v_lshl_add_u64 v[6:7], v[218:219], 0, s[14:15]
	s_barrier
	ds_read_b128 v[148:151], v197 offset:49152
	ds_read_b128 v[152:155], v197 offset:50176
	ds_read_b128 v[156:159], v197 offset:51200
	ds_read_b128 v[160:163], v197 offset:52224
	ds_read_b128 v[164:167], v197 offset:53248
	ds_read_b128 v[168:171], v197 offset:54272
	ds_read_b128 v[172:175], v197 offset:55296
	ds_read_b128 v[176:179], v197 offset:56320
	global_load_lds_dwordx4 v[6:7], off
	v_lshl_add_u64 v[6:7], v[220:221], 0, s[14:15]
	s_mov_b32 m0, s77
	s_nop 0
	global_load_lds_dwordx4 v[6:7], off
	s_barrier
	s_waitcnt lgkmcnt(0)

	s_waitcnt lgkmcnt(0)
	v_mfma_f32_16x16x32_bf16 v[60:63], v[132:135], v[148:151], v[60:63]
	v_mfma_f32_16x16x32_bf16 v[64:67], v[140:143], v[148:151], v[64:67]
	v_mfma_f32_16x16x32_bf16 v[44:47], v[132:135], v[156:159], v[44:47]
	v_mfma_f32_16x16x32_bf16 v[48:51], v[140:143], v[156:159], v[48:51]
	v_mfma_f32_16x16x32_bf16 v[28:31], v[132:135], v[164:167], v[28:31]
	v_mfma_f32_16x16x32_bf16 v[32:35], v[140:143], v[164:167], v[32:35]
	v_mfma_f32_16x16x32_bf16 v[12:15], v[132:135], v[172:175], v[12:15]
	v_mfma_f32_16x16x32_bf16 v[16:19], v[140:143], v[172:175], v[16:19]
	v_mfma_f32_16x16x32_bf16 v[60:63], v[136:139], v[152:155], v[60:63]
	v_mfma_f32_16x16x32_bf16 v[64:67], v[144:147], v[152:155], v[64:67]
	v_mfma_f32_16x16x32_bf16 v[44:47], v[136:139], v[160:163], v[44:47]
	v_mfma_f32_16x16x32_bf16 v[48:51], v[144:147], v[160:163], v[48:51]
	v_mfma_f32_16x16x32_bf16 v[28:31], v[136:139], v[168:171], v[28:31]
	v_mfma_f32_16x16x32_bf16 v[32:35], v[144:147], v[168:171], v[32:35]
	v_mfma_f32_16x16x32_bf16 v[12:15], v[136:139], v[176:179], v[12:15]
	v_mfma_f32_16x16x32_bf16 v[16:19], v[144:147], v[176:179], v[16:19]

	s_barrier
	s_add_i32 s3, s12, s67
	v_lshl_add_u64 v[6:7], v[222:223], 0, s[14:15]
	s_mov_b32 m0, s3
	s_nop 0
	global_load_lds_dwordx4 v[6:7], off
	v_lshl_add_u64 v[6:7], v[224:225], 0, s[14:15]
	s_add_i32 m0, s3, 0x2000
	s_nop 0
	global_load_lds_dwordx4 v[6:7], off
	s_waitcnt vmcnt(6)
	s_barrier

	v_mfma_f32_16x16x32_bf16 v[52:55], v[198:201], v[148:151], v[52:55]
	v_mfma_f32_16x16x32_bf16 v[56:59], v[206:209], v[148:151], v[56:59]
	v_mfma_f32_16x16x32_bf16 v[36:39], v[198:201], v[156:159], v[36:39]
	v_mfma_f32_16x16x32_bf16 v[40:43], v[206:209], v[156:159], v[40:43]
	v_mfma_f32_16x16x32_bf16 v[20:23], v[198:201], v[164:167], v[20:23]
	v_mfma_f32_16x16x32_bf16 v[24:27], v[206:209], v[164:167], v[24:27]
	v_mfma_f32_16x16x32_bf16 v[2:5], v[198:201], v[172:175], v[2:5]
	v_mfma_f32_16x16x32_bf16 v[8:11], v[206:209], v[172:175], v[8:11]
	v_mfma_f32_16x16x32_bf16 v[52:55], v[202:205], v[152:155], v[52:55]
	v_mfma_f32_16x16x32_bf16 v[56:59], v[210:213], v[152:155], v[56:59]
	v_mfma_f32_16x16x32_bf16 v[36:39], v[202:205], v[160:163], v[36:39]
	v_mfma_f32_16x16x32_bf16 v[40:43], v[210:213], v[160:163], v[40:43]
	v_mfma_f32_16x16x32_bf16 v[20:23], v[202:205], v[168:171], v[20:23]
	v_mfma_f32_16x16x32_bf16 v[24:27], v[210:213], v[168:171], v[24:27]
	v_mfma_f32_16x16x32_bf16 v[4:7], v[202:205], v[176:179], v[2:5]
	v_mfma_f32_16x16x32_bf16 v[8:11], v[210:213], v[176:179], v[8:11]

	s_add_u32 s58, s58, 0x100
	s_addc_u32 s59, s59, 0
	s_add_u32 s96, s96, 0x100
	s_addc_u32 s97, s97, 0
	s_cmp_ge_i32 s68, s78
	s_barrier
	s_cbranch_scc1 .LBB0_667

.Lprio_743:
	s_waitcnt vmcnt(4)
	v_mov_b32_e32 v12, v180
	s_waitcnt lgkmcnt(0)
	s_barrier
	s_movk_i32 s0, 0x400
	v_readfirstlane_b32 s16, v12
	s_and_b64 vcc, exec, s[4:5]
	s_cbranch_vccnz .LBB0_749
	s_ashr_i32 s1, s2, 31
	s_lshr_b32 s1, s1, 29
	s_add_i32 s8, s2, s1
	s_and_b32 s1, s8, -8
	s_sub_i32 s1, s2, s1
	s_cmp_gt_i32 s1, -1
	s_cbranch_scc0 .LBB0_746
	s_lshl_b32 s3, s1, 6
	s_ashr_i32 s6, s8, 3
	s_cbranch_execz .LBB0_747
	s_branch .LBB0_748

.LBB0_766:
	ds_read_b128 v[128:131], v215
	ds_read_b128 v[132:135], v215 offset:1024
	ds_read_b128 v[136:139], v215 offset:2048
	ds_read_b128 v[140:143], v215 offset:3072
	s_add_i32 s62, s24, 2
	s_add_u32 s26, s0, 0x80
	s_addc_u32 s25, s1, 0
	s_cmp_eq_u32 s51, s24
	s_cselect_b32 s24, s20, s26
	s_cselect_b32 s25, s21, s25
	s_cselect_b32 s27, s7, s61
	s_cselect_b32 s26, s6, s60
	v_lshl_add_u64 v[194:195], s[0:1], 0, v[186:187]
	s_add_i32 m0, s41, 0xc000
	ds_read_b128 v[144:147], v216
	ds_read_b128 v[148:151], v216 offset:1024
	ds_read_b128 v[152:155], v216 offset:2048
	ds_read_b128 v[156:159], v216 offset:3072
	ds_read_b128 v[160:163], v216 offset:4096
	ds_read_b128 v[164:167], v216 offset:5120
	ds_read_b128 v[168:171], v216 offset:6144
	ds_read_b128 v[172:175], v216 offset:7168
	global_load_lds_dwordx4 v[194:195], off
	v_lshl_add_u64 v[194:195], s[0:1], 0, v[188:189]
	s_add_i32 m0, s41, 0xe000
	s_nop 0
	global_load_lds_dwordx4 v[194:195], off
	s_waitcnt lgkmcnt(8)
	s_barrier
	s_waitcnt lgkmcnt(0)

	s_waitcnt lgkmcnt(0)
	v_mfma_f32_16x16x32_bf16 v[124:127], v[128:131], v[144:147], v[124:127]
	v_mfma_f32_16x16x32_bf16 v[120:123], v[136:139], v[144:147], v[120:123]
	v_mfma_f32_16x16x32_bf16 v[108:111], v[128:131], v[152:155], v[108:111]
	v_mfma_f32_16x16x32_bf16 v[104:107], v[136:139], v[152:155], v[104:107]
	v_mfma_f32_16x16x32_bf16 v[92:95], v[128:131], v[160:163], v[92:95]
	v_mfma_f32_16x16x32_bf16 v[88:91], v[136:139], v[160:163], v[88:91]
	v_mfma_f32_16x16x32_bf16 v[76:79], v[128:131], v[168:171], v[76:79]
	v_mfma_f32_16x16x32_bf16 v[72:75], v[136:139], v[168:171], v[72:75]
	v_mfma_f32_16x16x32_bf16 v[124:127], v[132:135], v[148:151], v[124:127]
	v_mfma_f32_16x16x32_bf16 v[120:123], v[140:143], v[148:151], v[120:123]
	v_mfma_f32_16x16x32_bf16 v[108:111], v[132:135], v[156:159], v[108:111]
	v_mfma_f32_16x16x32_bf16 v[104:107], v[140:143], v[156:159], v[104:107]
	v_mfma_f32_16x16x32_bf16 v[92:95], v[132:135], v[164:167], v[92:95]
	v_mfma_f32_16x16x32_bf16 v[88:91], v[140:143], v[164:167], v[88:91]
	v_mfma_f32_16x16x32_bf16 v[76:79], v[132:135], v[172:175], v[76:79]
	v_mfma_f32_16x16x32_bf16 v[72:75], v[140:143], v[172:175], v[72:75]

	s_barrier
	s_add_i32 s63, s55, s40
	v_lshl_add_u64 v[210:211], s[26:27], 0, v[178:179]
	s_mov_b32 m0, s63
	ds_read_b128 v[194:197], v217
	ds_read_b128 v[198:201], v217 offset:1024
	ds_read_b128 v[202:205], v217 offset:2048
	ds_read_b128 v[206:209], v217 offset:3072
	global_load_lds_dwordx4 v[210:211], off
	v_lshl_add_u64 v[218:219], s[26:27], 0, v[184:185]
	s_add_i32 m0, s63, 0x2000
	s_nop 0
	global_load_lds_dwordx4 v[218:219], off
	s_barrier
	s_waitcnt lgkmcnt(0)

	s_waitcnt lgkmcnt(0)
	v_mfma_f32_16x16x32_bf16 v[116:119], v[194:197], v[144:147], v[116:119]
	v_mfma_f32_16x16x32_bf16 v[112:115], v[202:205], v[144:147], v[112:115]
	v_mfma_f32_16x16x32_bf16 v[100:103], v[194:197], v[152:155], v[100:103]
	v_mfma_f32_16x16x32_bf16 v[96:99], v[202:205], v[152:155], v[96:99]
	v_mfma_f32_16x16x32_bf16 v[84:87], v[194:197], v[160:163], v[84:87]
	v_mfma_f32_16x16x32_bf16 v[80:83], v[202:205], v[160:163], v[80:83]
	v_mfma_f32_16x16x32_bf16 v[68:71], v[194:197], v[168:171], v[68:71]
	v_mfma_f32_16x16x32_bf16 v[64:67], v[202:205], v[168:171], v[64:67]
	v_mfma_f32_16x16x32_bf16 v[116:119], v[198:201], v[148:151], v[116:119]
	v_mfma_f32_16x16x32_bf16 v[112:115], v[206:209], v[148:151], v[112:115]
	v_mfma_f32_16x16x32_bf16 v[100:103], v[198:201], v[156:159], v[100:103]
	v_mfma_f32_16x16x32_bf16 v[96:99], v[206:209], v[156:159], v[96:99]
	v_mfma_f32_16x16x32_bf16 v[84:87], v[198:201], v[164:167], v[84:87]
	v_mfma_f32_16x16x32_bf16 v[80:83], v[206:209], v[164:167], v[80:83]
	v_mfma_f32_16x16x32_bf16 v[68:71], v[198:201], v[172:175], v[68:71]
	v_mfma_f32_16x16x32_bf16 v[64:67], v[206:209], v[172:175], v[64:67]

	s_mov_b32 m0, s41
	v_lshl_add_u64 v[220:221], s[24:25], 0, v[176:177]
	s_barrier
	ds_read_b128 v[144:147], v216 offset:16384
	ds_read_b128 v[148:151], v216 offset:17408
	ds_read_b128 v[152:155], v216 offset:18432
	ds_read_b128 v[156:159], v216 offset:19456
	ds_read_b128 v[160:163], v216 offset:20480
	ds_read_b128 v[164:167], v216 offset:21504
	ds_read_b128 v[168:171], v216 offset:22528
	ds_read_b128 v[172:175], v216 offset:23552
	global_load_lds_dwordx4 v[220:221], off
	v_lshl_add_u64 v[222:223], s[24:25], 0, v[182:183]
	s_mov_b32 m0, s42
	s_nop 0
	global_load_lds_dwordx4 v[222:223], off
	s_barrier
	s_waitcnt lgkmcnt(0)

	s_waitcnt lgkmcnt(0)
	v_mfma_f32_16x16x32_bf16 v[60:63], v[128:131], v[144:147], v[60:63]
	v_mfma_f32_16x16x32_bf16 v[56:59], v[136:139], v[144:147], v[56:59]
	v_mfma_f32_16x16x32_bf16 v[44:47], v[128:131], v[152:155], v[44:47]
	v_mfma_f32_16x16x32_bf16 v[40:43], v[136:139], v[152:155], v[40:43]
	v_mfma_f32_16x16x32_bf16 v[28:31], v[128:131], v[160:163], v[28:31]
	v_mfma_f32_16x16x32_bf16 v[24:27], v[136:139], v[160:163], v[24:27]
	v_mfma_f32_16x16x32_bf16 v[12:15], v[128:131], v[168:171], v[12:15]
	v_mfma_f32_16x16x32_bf16 v[8:11], v[136:139], v[168:171], v[8:11]
	v_mfma_f32_16x16x32_bf16 v[60:63], v[132:135], v[148:151], v[60:63]
	v_mfma_f32_16x16x32_bf16 v[56:59], v[140:143], v[148:151], v[56:59]
	v_mfma_f32_16x16x32_bf16 v[44:47], v[132:135], v[156:159], v[44:47]
	v_mfma_f32_16x16x32_bf16 v[40:43], v[140:143], v[156:159], v[40:43]
	v_mfma_f32_16x16x32_bf16 v[28:31], v[132:135], v[164:167], v[28:31]
	v_mfma_f32_16x16x32_bf16 v[24:27], v[140:143], v[164:167], v[24:27]
	v_mfma_f32_16x16x32_bf16 v[12:15], v[132:135], v[172:175], v[12:15]
	v_mfma_f32_16x16x32_bf16 v[8:11], v[140:143], v[172:175], v[8:11]

	s_barrier
	s_add_u32 s26, s26, s8
	s_addc_u32 s27, s27, s9
	s_add_i32 s63, s56, s40
	v_lshl_add_u64 v[224:225], s[26:27], 0, v[178:179]
	s_mov_b32 m0, s63
	v_lshl_add_u64 v[226:227], s[26:27], 0, v[184:185]
	global_load_lds_dwordx4 v[224:225], off
	s_add_i32 m0, s63, 0x2000
	s_nop 0
	global_load_lds_dwordx4 v[226:227], off
	s_waitcnt vmcnt(6)
	s_barrier

	v_mfma_f32_16x16x32_bf16 v[52:55], v[194:197], v[144:147], v[52:55]
	v_mfma_f32_16x16x32_bf16 v[48:51], v[202:205], v[144:147], v[48:51]
	v_mfma_f32_16x16x32_bf16 v[36:39], v[194:197], v[152:155], v[36:39]
	v_mfma_f32_16x16x32_bf16 v[32:35], v[202:205], v[152:155], v[32:35]
	v_mfma_f32_16x16x32_bf16 v[20:23], v[194:197], v[160:163], v[20:23]
	v_mfma_f32_16x16x32_bf16 v[16:19], v[202:205], v[160:163], v[16:19]
	v_mfma_f32_16x16x32_bf16 v[4:7], v[194:197], v[168:171], v[4:7]
	v_mfma_f32_16x16x32_bf16 v[0:3], v[202:205], v[168:171], v[0:3]
	v_mfma_f32_16x16x32_bf16 v[52:55], v[198:201], v[148:151], v[52:55]
	v_mfma_f32_16x16x32_bf16 v[48:51], v[206:209], v[148:151], v[48:51]
	v_mfma_f32_16x16x32_bf16 v[36:39], v[198:201], v[156:159], v[36:39]
	v_mfma_f32_16x16x32_bf16 v[32:35], v[206:209], v[156:159], v[32:35]
	v_mfma_f32_16x16x32_bf16 v[20:23], v[198:201], v[164:167], v[20:23]
	v_mfma_f32_16x16x32_bf16 v[16:19], v[206:209], v[164:167], v[16:19]
	v_mfma_f32_16x16x32_bf16 v[4:7], v[198:201], v[172:175], v[4:7]
	v_mfma_f32_16x16x32_bf16 v[0:3], v[206:209], v[172:175], v[0:3]

	s_add_i32 s26, 0, 0x18000
	v_add_u32_e32 v140, s26, v214
	s_barrier
	ds_read_b128 v[128:131], v140
	ds_read_b128 v[132:135], v140 offset:1024
	ds_read_b128 v[136:139], v140 offset:2048
	ds_read_b128 v[140:143], v140 offset:3072
	s_add_u32 s24, s24, s8
	s_addc_u32 s25, s25, s9
	s_mov_b32 m0, s43
	v_lshl_add_u64 v[194:195], s[24:25], 0, v[176:177]
	ds_read_b128 v[144:147], v216 offset:32768
	ds_read_b128 v[148:151], v216 offset:33792
	ds_read_b128 v[152:155], v216 offset:34816
	ds_read_b128 v[156:159], v216 offset:35840
	ds_read_b128 v[160:163], v216 offset:36864
	ds_read_b128 v[164:167], v216 offset:37888
	ds_read_b128 v[168:171], v216 offset:38912
	ds_read_b128 v[172:175], v216 offset:39936
	global_load_lds_dwordx4 v[194:195], off
	v_lshl_add_u64 v[194:195], s[24:25], 0, v[182:183]
	s_mov_b32 m0, s44
	s_nop 0
	global_load_lds_dwordx4 v[194:195], off
	s_waitcnt lgkmcnt(8)
	s_barrier
	s_waitcnt lgkmcnt(0)

	s_waitcnt lgkmcnt(0)
	v_mfma_f32_16x16x32_bf16 v[124:127], v[128:131], v[144:147], v[124:127]
	v_mfma_f32_16x16x32_bf16 v[120:123], v[136:139], v[144:147], v[120:123]
	v_mfma_f32_16x16x32_bf16 v[108:111], v[128:131], v[152:155], v[108:111]
	v_mfma_f32_16x16x32_bf16 v[104:107], v[136:139], v[152:155], v[104:107]
	v_mfma_f32_16x16x32_bf16 v[92:95], v[128:131], v[160:163], v[92:95]
	v_mfma_f32_16x16x32_bf16 v[88:91], v[136:139], v[160:163], v[88:91]
	v_mfma_f32_16x16x32_bf16 v[76:79], v[128:131], v[168:171], v[76:79]
	v_mfma_f32_16x16x32_bf16 v[72:75], v[136:139], v[168:171], v[72:75]
	v_mfma_f32_16x16x32_bf16 v[124:127], v[132:135], v[148:151], v[124:127]
	v_mfma_f32_16x16x32_bf16 v[120:123], v[140:143], v[148:151], v[120:123]
	v_mfma_f32_16x16x32_bf16 v[108:111], v[132:135], v[156:159], v[108:111]
	v_mfma_f32_16x16x32_bf16 v[104:107], v[140:143], v[156:159], v[104:107]
	v_mfma_f32_16x16x32_bf16 v[92:95], v[132:135], v[164:167], v[92:95]
	v_mfma_f32_16x16x32_bf16 v[88:91], v[140:143], v[164:167], v[88:91]
	v_mfma_f32_16x16x32_bf16 v[76:79], v[132:135], v[172:175], v[76:79]
	v_mfma_f32_16x16x32_bf16 v[72:75], v[140:143], v[172:175], v[72:75]

	s_barrier
	s_add_i32 s24, 0, 0x1c000
	s_add_i32 s25, s26, s40
	v_add_u32_e32 v206, s24, v214
	v_lshl_add_u64 v[210:211], v[210:211], 0, s[12:13]
	s_mov_b32 m0, s25
	ds_read_b128 v[194:197], v206
	ds_read_b128 v[198:201], v206 offset:1024
	ds_read_b128 v[202:205], v206 offset:2048
	ds_read_b128 v[206:209], v206 offset:3072
	global_load_lds_dwordx4 v[210:211], off
	v_lshl_add_u64 v[210:211], v[218:219], 0, s[12:13]
	s_add_i32 m0, s25, 0x2000
	s_nop 0
	global_load_lds_dwordx4 v[210:211], off
	s_barrier
	s_waitcnt lgkmcnt(0)

	s_waitcnt lgkmcnt(0)
	v_mfma_f32_16x16x32_bf16 v[116:119], v[194:197], v[144:147], v[116:119]
	v_mfma_f32_16x16x32_bf16 v[112:115], v[202:205], v[144:147], v[112:115]
	v_mfma_f32_16x16x32_bf16 v[100:103], v[194:197], v[152:155], v[100:103]
	v_mfma_f32_16x16x32_bf16 v[96:99], v[202:205], v[152:155], v[96:99]
	v_mfma_f32_16x16x32_bf16 v[84:87], v[194:197], v[160:163], v[84:87]
	v_mfma_f32_16x16x32_bf16 v[80:83], v[202:205], v[160:163], v[80:83]
	v_mfma_f32_16x16x32_bf16 v[68:71], v[194:197], v[168:171], v[68:71]
	v_mfma_f32_16x16x32_bf16 v[64:67], v[202:205], v[168:171], v[64:67]
	v_mfma_f32_16x16x32_bf16 v[116:119], v[198:201], v[148:151], v[116:119]
	v_mfma_f32_16x16x32_bf16 v[112:115], v[206:209], v[148:151], v[112:115]
	v_mfma_f32_16x16x32_bf16 v[100:103], v[198:201], v[156:159], v[100:103]
	v_mfma_f32_16x16x32_bf16 v[96:99], v[206:209], v[156:159], v[96:99]
	v_mfma_f32_16x16x32_bf16 v[84:87], v[198:201], v[164:167], v[84:87]
	v_mfma_f32_16x16x32_bf16 v[80:83], v[206:209], v[164:167], v[80:83]
	v_mfma_f32_16x16x32_bf16 v[68:71], v[198:201], v[172:175], v[68:71]
	v_mfma_f32_16x16x32_bf16 v[64:67], v[206:209], v[172:175], v[64:67]

	s_mov_b32 m0, s46
	v_lshl_add_u64 v[210:211], v[220:221], 0, s[12:13]
	s_barrier
	ds_read_b128 v[144:147], v216 offset:49152
	ds_read_b128 v[148:151], v216 offset:50176
	ds_read_b128 v[152:155], v216 offset:51200
	ds_read_b128 v[156:159], v216 offset:52224
	ds_read_b128 v[160:163], v216 offset:53248
	ds_read_b128 v[164:167], v216 offset:54272
	ds_read_b128 v[168:171], v216 offset:55296
	ds_read_b128 v[172:175], v216 offset:56320
	global_load_lds_dwordx4 v[210:211], off
	v_lshl_add_u64 v[210:211], v[222:223], 0, s[12:13]
	s_mov_b32 m0, s47
	s_nop 0
	global_load_lds_dwordx4 v[210:211], off
	s_barrier
	s_waitcnt lgkmcnt(0)

	s_waitcnt lgkmcnt(0)
	v_mfma_f32_16x16x32_bf16 v[60:63], v[128:131], v[144:147], v[60:63]
	v_mfma_f32_16x16x32_bf16 v[56:59], v[136:139], v[144:147], v[56:59]
	v_mfma_f32_16x16x32_bf16 v[44:47], v[128:131], v[152:155], v[44:47]
	v_mfma_f32_16x16x32_bf16 v[40:43], v[136:139], v[152:155], v[40:43]
	v_mfma_f32_16x16x32_bf16 v[28:31], v[128:131], v[160:163], v[28:31]
	v_mfma_f32_16x16x32_bf16 v[24:27], v[136:139], v[160:163], v[24:27]
	v_mfma_f32_16x16x32_bf16 v[12:15], v[128:131], v[168:171], v[12:15]
	v_mfma_f32_16x16x32_bf16 v[8:11], v[136:139], v[168:171], v[8:11]
	v_mfma_f32_16x16x32_bf16 v[60:63], v[132:135], v[148:151], v[60:63]
	v_mfma_f32_16x16x32_bf16 v[56:59], v[140:143], v[148:151], v[56:59]
	v_mfma_f32_16x16x32_bf16 v[44:47], v[132:135], v[156:159], v[44:47]
	v_mfma_f32_16x16x32_bf16 v[40:43], v[140:143], v[156:159], v[40:43]
	v_mfma_f32_16x16x32_bf16 v[28:31], v[132:135], v[164:167], v[28:31]
	v_mfma_f32_16x16x32_bf16 v[24:27], v[140:143], v[164:167], v[24:27]
	v_mfma_f32_16x16x32_bf16 v[12:15], v[132:135], v[172:175], v[12:15]
	v_mfma_f32_16x16x32_bf16 v[8:11], v[140:143], v[172:175], v[8:11]

	s_barrier
	s_add_i32 s24, s24, s40
	v_lshl_add_u64 v[128:129], v[224:225], 0, s[12:13]
	s_mov_b32 m0, s24
	s_nop 0
	global_load_lds_dwordx4 v[128:129], off
	v_lshl_add_u64 v[128:129], v[226:227], 0, s[12:13]
	s_add_i32 m0, s24, 0x2000
	s_nop 0
	global_load_lds_dwordx4 v[128:129], off
	s_waitcnt vmcnt(6)
	s_barrier

	v_mfma_f32_16x16x32_bf16 v[52:55], v[194:197], v[144:147], v[52:55]
	v_mfma_f32_16x16x32_bf16 v[48:51], v[202:205], v[144:147], v[48:51]
	v_mfma_f32_16x16x32_bf16 v[36:39], v[194:197], v[152:155], v[36:39]
	v_mfma_f32_16x16x32_bf16 v[32:35], v[202:205], v[152:155], v[32:35]
	v_mfma_f32_16x16x32_bf16 v[20:23], v[194:197], v[160:163], v[20:23]
	v_mfma_f32_16x16x32_bf16 v[16:19], v[202:205], v[160:163], v[16:19]
	v_mfma_f32_16x16x32_bf16 v[4:7], v[194:197], v[168:171], v[4:7]
	v_mfma_f32_16x16x32_bf16 v[0:3], v[202:205], v[168:171], v[0:3]
	v_mfma_f32_16x16x32_bf16 v[52:55], v[198:201], v[148:151], v[52:55]
	v_mfma_f32_16x16x32_bf16 v[48:51], v[206:209], v[148:151], v[48:51]
	v_mfma_f32_16x16x32_bf16 v[36:39], v[198:201], v[156:159], v[36:39]
	v_mfma_f32_16x16x32_bf16 v[32:35], v[206:209], v[156:159], v[32:35]
	v_mfma_f32_16x16x32_bf16 v[20:23], v[198:201], v[164:167], v[20:23]
	v_mfma_f32_16x16x32_bf16 v[16:19], v[206:209], v[164:167], v[16:19]
	v_mfma_f32_16x16x32_bf16 v[4:7], v[198:201], v[172:175], v[4:7]
	v_mfma_f32_16x16x32_bf16 v[0:3], v[206:209], v[172:175], v[0:3]

	s_add_u32 s0, s0, 0x100
	s_addc_u32 s1, s1, 0
	s_add_u32 s60, s60, 0x100
	s_addc_u32 s61, s61, 0
	s_cmp_ge_i32 s62, s48
	s_mov_b32 s24, s62
	s_barrier
	s_cbranch_scc0 .LBB0_766

.LBB0_838:
	s_or_b64 exec, exec, s[0:1]
	s_setprio 0
	s_mov_b32 s3, 0
	s_waitcnt lgkmcnt(0)
	s_barrier
	s_lshl_b64 s[0:1], s[2:3], 9
	s_mov_b64 s[6:7], 0x800000
	v_ashrrev_i32_e32 v181, 31, v180
	v_lshl_add_u64 v[0:1], s[0:1], 0, v[180:181]
	v_cmp_gt_u64_e32 vcc, s[6:7], v[0:1]
	s_and_saveexec_b64 s[0:1], vcc
	s_cbranch_execz .LBB0_845
	s_mov_b32 s19, s3
	s_lshl_b64 s[0:1], s[2:3], 11
	s_lshl_b64 s[8:9], s[18:19], 9
	v_lshl_add_u64 v[12:13], v[180:181], 2, s[0:1]
	s_lshl_b64 s[10:11], s[18:19], 13
	s_lshl_b64 s[12:13], s[18:19], 10
	s_lshl_b64 s[0:1], s[18:19], 14
	s_add_u32 s14, s30, s0
	s_addc_u32 s15, s31, s1
	s_lshl_b64 s[0:1], s[2:3], 13
	s_waitcnt vmcnt(3)
	v_lshl_add_u64 v[14:15], v[180:181], 4, s[0:1]
	s_lshl_b64 s[16:17], s[18:19], 15
	s_mul_i32 s1, s18, 0x6000
	s_mul_hi_u32 s21, s18, 0x600
	s_mul_i32 s20, s18, 0x600
	s_mul_hi_u32 s0, s18, 0x6000
	s_add_u32 s18, s30, s1
	s_addc_u32 s19, s31, s0
	s_add_u32 s22, s30, s10
	s_addc_u32 s23, s31, s11
	s_mov_b64 s[24:25], 0
	v_mov_b32_e32 v22, 0x358637bd
	s_mov_b32 s33, 0x800000
	s_waitcnt vmcnt(1)
	v_mov_b32_e32 v17, 0
	s_mov_b64 s[26:27], 0x7fffff
	s_branch .LBB0_841
